# acc-paired MFMA order + P4 reversed rounds; P4 main loop re-aligned to its baseline placement
# baseline (speedup 1.0000x reference)
; template <class Epi, class Ptrs>
; __device__ __forceinline__ void gemm_phase(LAS unsigned char* lds, const int K, const StaticOrder& S, const Ptrs& P, const Epi& E) {
;     ...
; #pragma unroll
;         for (int a = 0; a < 2; ++a)
; #pragma unroll
;             for (int b = 0; b < 2; ++b)
; #pragma unroll
;                 for (int m = 0; m < 4; ++m)
; #pragma unroll
;                     for (int n = 0; n < 2; ++n) acc[a][b][m][n] = (f32x4){0.f, 0.f, 0.f, 0.f};
;         cur = nxt; cA = nA; cB = nB; ++ui;
.LBB0_432:
	s_nop 0
	s_nop 0
	s_nop 0
	s_nop 0
	s_nop 0
	s_nop 0
	s_nop 0
	s_nop 0
	s_nop 0
	s_nop 0
	s_nop 0
	s_nop 0
	s_nop 0
	s_nop 0
	s_nop 0
	s_nop 0
	s_nop 0
	s_nop 0
	s_nop 0
	s_nop 0
	s_nop 0
	s_nop 0
	s_nop 0
	s_nop 0
	s_nop 0
	s_nop 0
	s_nop 0
	s_nop 0
	s_nop 0
	s_nop 0
	s_nop 0
	s_nop 0
	s_nop 0
	s_nop 0
	s_nop 0
	s_nop 0
	s_nop 0
	s_nop 0
	s_nop 0
	s_nop 0
	s_nop 0
	s_nop 0
	s_nop 0
	s_nop 0
	s_nop 0
	s_nop 0
	s_nop 0
	s_nop 0
	s_nop 0
	s_nop 0
	s_nop 0
	s_nop 0
	s_nop 0
	s_nop 0
	s_nop 0
	s_nop 0
	s_nop 0
	s_nop 0
	s_nop 0
	s_nop 0
	s_nop 0
	s_add_u32 s40, s40, 0x40080
	s_addc_u32 s41, s41, 0
	s_add_u32 s23, s42, 0x100
	v_mov_b32_e32 v0, 0
	s_addc_u32 s25, s43, 0
	s_mov_b32 s70, -2
	v_mov_b32_e32 v1, v0
	v_mov_b32_e32 v2, v0
	v_mov_b32_e32 v3, v0
	v_mov_b32_e32 v4, v0
	v_mov_b32_e32 v5, v0
	v_mov_b32_e32 v6, v0
	v_mov_b32_e32 v7, v0
	v_mov_b32_e32 v16, v0
	v_mov_b32_e32 v17, v0
	v_mov_b32_e32 v18, v0
	v_mov_b32_e32 v19, v0
	v_mov_b32_e32 v20, v0
	v_mov_b32_e32 v21, v0
	v_mov_b32_e32 v22, v0
	v_mov_b32_e32 v23, v0
	v_mov_b32_e32 v32, v0
	v_mov_b32_e32 v33, v0
	v_mov_b32_e32 v34, v0
	v_mov_b32_e32 v35, v0
	v_mov_b32_e32 v36, v0
	v_mov_b32_e32 v37, v0
	v_mov_b32_e32 v38, v0
	v_mov_b32_e32 v39, v0
	v_mov_b32_e32 v48, v0
	v_mov_b32_e32 v49, v0
	v_mov_b32_e32 v50, v0
	v_mov_b32_e32 v51, v0
	v_mov_b32_e32 v52, v0
	v_mov_b32_e32 v53, v0
	v_mov_b32_e32 v54, v0
	v_mov_b32_e32 v55, v0
	v_mov_b32_e32 v8, v0
	v_mov_b32_e32 v9, v0
	v_mov_b32_e32 v10, v0
	v_mov_b32_e32 v11, v0
	v_mov_b32_e32 v12, v0
	v_mov_b32_e32 v13, v0
	v_mov_b32_e32 v14, v0
	v_mov_b32_e32 v15, v0
	v_mov_b32_e32 v24, v0
	v_mov_b32_e32 v25, v0
	v_mov_b32_e32 v26, v0
	v_mov_b32_e32 v27, v0
	v_mov_b32_e32 v28, v0
	v_mov_b32_e32 v29, v0
	v_mov_b32_e32 v30, v0
	v_mov_b32_e32 v31, v0
	v_mov_b32_e32 v40, v0
	v_mov_b32_e32 v41, v0
	v_mov_b32_e32 v42, v0
	v_mov_b32_e32 v43, v0
	v_mov_b32_e32 v44, v0
	v_mov_b32_e32 v45, v0
	v_mov_b32_e32 v46, v0
	v_mov_b32_e32 v47, v0
	v_mov_b32_e32 v56, v0
	v_mov_b32_e32 v57, v0
	v_mov_b32_e32 v58, v0
	v_mov_b32_e32 v59, v0
	v_mov_b32_e32 v60, v0
	v_mov_b32_e32 v61, v0
	v_mov_b32_e32 v62, v0
	v_mov_b32_e32 v63, v0
	v_mov_b32_e32 v64, v0
	v_mov_b32_e32 v65, v0
	v_mov_b32_e32 v66, v0
	v_mov_b32_e32 v67, v0
	v_mov_b32_e32 v68, v0
	v_mov_b32_e32 v69, v0
	v_mov_b32_e32 v70, v0
	v_mov_b32_e32 v71, v0
	v_mov_b32_e32 v80, v0
	v_mov_b32_e32 v81, v0
	v_mov_b32_e32 v82, v0
	v_mov_b32_e32 v83, v0
	v_mov_b32_e32 v84, v0
	v_mov_b32_e32 v85, v0
	v_mov_b32_e32 v86, v0
	v_mov_b32_e32 v87, v0
	v_mov_b32_e32 v96, v0
	v_mov_b32_e32 v97, v0
	v_mov_b32_e32 v98, v0
	v_mov_b32_e32 v99, v0
	v_mov_b32_e32 v100, v0
	v_mov_b32_e32 v101, v0
	v_mov_b32_e32 v102, v0
	v_mov_b32_e32 v103, v0
	v_mov_b32_e32 v112, v0
	v_mov_b32_e32 v113, v0
	v_mov_b32_e32 v114, v0
	v_mov_b32_e32 v115, v0
	v_mov_b32_e32 v116, v0
	v_mov_b32_e32 v117, v0
	v_mov_b32_e32 v118, v0
	v_mov_b32_e32 v119, v0
	v_mov_b32_e32 v72, v0
	v_mov_b32_e32 v73, v0
	v_mov_b32_e32 v74, v0
	v_mov_b32_e32 v75, v0
	v_mov_b32_e32 v76, v0
	v_mov_b32_e32 v77, v0
	v_mov_b32_e32 v78, v0
	v_mov_b32_e32 v79, v0
	v_mov_b32_e32 v88, v0
	v_mov_b32_e32 v89, v0
	v_mov_b32_e32 v90, v0
	v_mov_b32_e32 v91, v0
	v_mov_b32_e32 v92, v0
	v_mov_b32_e32 v93, v0
	v_mov_b32_e32 v94, v0
	v_mov_b32_e32 v95, v0
	v_mov_b32_e32 v104, v0
	v_mov_b32_e32 v105, v0
	v_mov_b32_e32 v106, v0
	v_mov_b32_e32 v107, v0
	v_mov_b32_e32 v108, v0
	v_mov_b32_e32 v109, v0
	v_mov_b32_e32 v110, v0
	v_mov_b32_e32 v111, v0
	v_mov_b32_e32 v120, v0
	v_mov_b32_e32 v121, v0
	v_mov_b32_e32 v122, v0
	v_mov_b32_e32 v123, v0
	v_mov_b32_e32 v124, v0
	v_mov_b32_e32 v125, v0
	v_mov_b32_e32 v126, v0
	v_mov_b32_e32 v127, v0
